# v2 + barrier exit no longer waits for the unobserved generation atomic; redundant vmcnt(0) drains behind 6 GEMM prologues relaxed to vmcnt(6)
# speedup vs baseline: 1.0065x; 1.0065x over previous
; __device__ __forceinline__ unsigned xb_ld(unsigned* p)              { return __hip_atomic_load(p, __ATOMIC_RELAXED, __HIP_MEMORY_SCOPE_AGENT); }
; __device__ __forceinline__ unsigned xb_add(unsigned* p, unsigned v) { return __hip_atomic_fetch_add(p, v, __ATOMIC_RELAXED, __HIP_MEMORY_SCOPE_AGENT); }
; #define XB_SPIN(cond, bar) do { unsigned _sp = 0; while (cond) { __builtin_amdgcn_s_sleep(1); \
;     if ((++_sp & 255u) == 0u) { if (xb_ld(&(bar)[XB_TMO])) break; if (_sp > XB_SPIN_CAP) { atomicAdd(&(bar)[XB_TMO], 1u); break; } } } } while (0)
; __device__ __forceinline__ void xcd_barrier_local(const XcdBarrier& b) {
;     ...
;         if (old + 1u == target) (void)xb_add(&bar[XB_XGEN(b.x)], 1u);
;         else XB_SPIN(xb_ld(&bar[XB_XSUB(b.x)]) < target, bar);
;         __builtin_amdgcn_fence(__ATOMIC_ACQUIRE, "agent");
;         asm volatile("s_waitcnt vmcnt(0)" ::: "memory");
;     }
.LBB0_875:
	s_or_b64 exec, exec, s[2:3]
.LBB0_876:
	s_or_b64 exec, exec, s[6:7]

; __device__ __forceinline__ unsigned xb_ld(unsigned* p)              { return __hip_atomic_load(p, __ATOMIC_RELAXED, __HIP_MEMORY_SCOPE_AGENT); }
; __device__ __forceinline__ unsigned xb_add(unsigned* p, unsigned v) { return __hip_atomic_fetch_add(p, v, __ATOMIC_RELAXED, __HIP_MEMORY_SCOPE_AGENT); }
; #define XB_SPIN(cond, bar) do { unsigned _sp = 0; while (cond) { __builtin_amdgcn_s_sleep(1); \
;     if ((++_sp & 255u) == 0u) { if (xb_ld(&(bar)[XB_TMO])) break; if (_sp > XB_SPIN_CAP) { atomicAdd(&(bar)[XB_TMO], 1u); break; } } } } while (0)
; __device__ __forceinline__ void xcd_barrier_local(const XcdBarrier& b) {
;     ...
;         if (old + 1u == target) (void)xb_add(&bar[XB_XGEN(b.x)], 1u);
;         else XB_SPIN(xb_ld(&bar[XB_XSUB(b.x)]) < target, bar);
;         __builtin_amdgcn_fence(__ATOMIC_ACQUIRE, "agent");
;         asm volatile("s_waitcnt vmcnt(0)" ::: "memory");
;     }
.LBB0_972:
	s_or_b64 exec, exec, s[2:3]
.LBB0_973:
	s_or_b64 exec, exec, s[6:7]

; #define PG8_STAGE(bufoff, gbase, voff) do { _Pragma("unroll") for (int _i = 0; _i < 2; ++_i) \
;         __builtin_amdgcn_global_load_lds((const unsigned*)((const char*)(gbase) + (voff)[_i]), (PG8_LAS unsigned*)(lds + (bufoff) + ldsw + _i * 8192), 16, 0, 0); } while (0)
; #define PG8_WAIT_V(n) asm volatile("s_waitcnt vmcnt(" #n ")" ::: "memory")
; #define PG8_BAR __builtin_amdgcn_s_barrier()
; #define LAS __attribute__((address_space(3)))
; template <class Epi, class Sched, bool ALIGN_EPI = false, bool SP2 = false>
; __device__ __forceinline__ void gemm_phase(PG8_LAS unsigned char* lds, const Gemm g, const Sched& S, const Epi& E, const int wave_id) {
;     ...
;         PG8_STAGE(PG8_SB(0, 0), cB, voffB); PG8_STAGE(PG8_SB(0, 1), cB + hstep, voffB); PG8_STAGE(PG8_SA(0, 0), cA, voffA); PG8_STAGE(PG8_SA(0, 1), cA + hstep, voffA);
;         if (wr == 1) PG8_BAR;
;         PG8_WAIT_V(2); PG8_BAR;
;         PG8_STAGE(PG8_SB(1, 0), cB + kstep, voffB); PG8_STAGE(PG8_SA(1, 0), cA + kstep, voffA); PG8_STAGE(PG8_SB(1, 1), cB + hstep + kstep, voffB);
;         PG8_WAIT_V(6); PG8_BAR;
;     } else {
;         PG8_STAGE(PG8_SB(0, 0), cB, voffB); PG8_STAGE(PG8_SA(0, 0), cA, voffA); PG8_STAGE(PG8_SB(0, 1), cB + hstep, voffB); PG8_STAGE(PG8_SA(0, 1), cA + hstep, voffA);
;         if (wr == 1) PG8_BAR;
;         PG8_WAIT_V(4); PG8_BAR;
;         PG8_STAGE(PG8_SB(1, 0), cB + kstep, voffB); PG8_STAGE(PG8_SA(1, 0), cA + kstep, voffA); PG8_STAGE(PG8_SB(1, 1), cB + hstep + kstep, voffB);
;         PG8_WAIT_V(6); PG8_BAR;
;     }
;     if constexpr (Epi::INIT_ACC) E.init_finish(acc, acc0);
;     __device__ __forceinline__ void pre_finish(const f32x4 (&p)[4], const float (&c)[3], int tid) const {
;         if (tid < 256) { const f32x4 s4 = (p[0] + p[1]) + (p[2] + p[3]); ((LAS float*)rtab)[tid] = rsqrtf(((s4[0] + s4[1]) + (s4[2] + s4[3])) * (1.0f / D) + EPS); }
;     }
.LBB0_1019:
	v_mov_b32_e32 v135, v201
	v_lshl_add_u64 v[24:25], s[14:15], 0, v[134:135]
	v_mov_b32_e32 v139, v201
	v_lshl_add_u64 v[26:27], s[14:15], 0, v[138:139]
	v_mov_b32_e32 v133, v201
	s_add_i32 m0, s67, 0x18000
	v_lshl_add_u64 v[24:25], v[24:25], 0, s[88:89]
	v_lshl_add_u64 v[28:29], s[12:13], 0, v[132:133]
	v_mov_b32_e32 v137, v201
	s_waitcnt vmcnt(2)
	s_barrier
	global_load_lds_dwordx4 v[24:25], off
	v_lshl_add_u64 v[24:25], v[26:27], 0, s[88:89]
	s_add_i32 m0, s67, 0x1a000
	s_add_i32 s73, s67, 0x8000
	s_add_i32 s74, s67, 0xa000
	v_lshl_add_u64 v[30:31], s[12:13], 0, v[136:137]
	global_load_lds_dwordx4 v[24:25], off
	v_lshl_add_u64 v[24:25], v[28:29], 0, s[88:89]
	s_mov_b32 m0, s73
	s_add_u32 s6, s14, 0x40080
	global_load_lds_dwordx4 v[24:25], off
	v_lshl_add_u64 v[24:25], v[30:31], 0, s[88:89]
	s_mov_b32 m0, s74
	s_addc_u32 s7, s15, 0
	global_load_lds_dwordx4 v[24:25], off
	s_add_i32 m0, s67, 0x1c000
	v_lshl_add_u64 v[24:25], s[6:7], 0, v[134:135]
	global_load_lds_dwordx4 v[24:25], off
	v_lshl_add_u64 v[24:25], s[6:7], 0, v[138:139]
	s_add_i32 m0, s67, 0x1e000
	s_nop 0
	global_load_lds_dwordx4 v[24:25], off
	s_waitcnt vmcnt(6)
	s_barrier
	s_and_saveexec_b64 s[6:7], vcc
	s_cbranch_execz .LBB0_1021
	s_waitcnt vmcnt(6)
	v_pk_add_f32 v[8:9], v[8:9], v[12:13]
	v_pk_add_f32 v[10:11], v[10:11], v[14:15]
	v_pk_add_f32 v[0:1], v[0:1], v[4:5]
	v_pk_add_f32 v[2:3], v[2:3], v[6:7]
	v_pk_add_f32 v[0:1], v[0:1], v[8:9]
	v_pk_add_f32 v[2:3], v[2:3], v[10:11]
	s_mov_b32 s9, 0x800000
	v_pk_mov_b32 v[4:5], v[0:1], v[2:3] op_sel:[1,0]
	v_mov_b32_e32 v1, v3
	v_pk_add_f32 v[0:1], v[4:5], v[0:1]
	s_nop 0
	v_add_f32_e32 v0, v0, v1
	v_mov_b32_e32 v1, 0x358637bd
	v_fmamk_f32 v0, v0, 0x3a800000, v1
	v_mul_f32_e32 v1, 0x4b800000, v0
	v_cmp_gt_f32_e32 vcc, s9, v0
	s_nop 1
	v_cndmask_b32_e32 v0, v0, v1, vcc
	v_rsq_f32_e32 v0, v0
	s_nop 0
	v_mul_f32_e32 v1, 0x45800000, v0
	v_cndmask_b32_e32 v0, v0, v1, vcc
	v_lshl_add_u32 v1, v16, 2, 0
	v_add_u32_e32 v1, 0x22400, v1
	ds_write_b32 v1, v0
.LBB0_1021:
	s_or_b64 exec, exec, s[6:7]
	s_ashr_i32 s75, s62, 31
	v_bfe_u32 v155, v16, 4, 2
	s_add_u32 s30, s18, 0xec00000
	v_and_b32_e32 v154, 15, v16
	s_waitcnt vmcnt(6)
	v_lshlrev_b32_e32 v0, 4, v155
	v_lshlrev_b32_e32 v1, 2, v16
	s_addc_u32 s31, s19, 0
	s_and_b32 s76, s1, 3
	v_lshl_or_b32 v0, v154, 6, v0
	s_lshl_b32 s1, s16, 13
	v_and_b32_e32 v1, 32, v1
	s_lshl_b32 s77, s16, 6
	v_bitop3_b32 v2, v0, s1, v1 bitop3:0xde
	s_lshl_b32 s78, s76, 5
	s_lshl_b32 s1, s76, 12
	s_add_u32 s79, s18, 0x8c00000
	s_addc_u32 s80, s19, 0
	s_add_u32 s34, s18, 0x8a00000
	v_bitop3_b32 v156, v0, s1, v1 bitop3:0xde
	s_addc_u32 s35, s19, 0
	s_mul_i32 s6, s86, 0x78000
	v_lshlrev_b32_e32 v0, 14, v17
	s_mul_hi_u32 s1, s86, 0x78000
	s_add_u32 s6, s24, s6
	v_and_b32_e32 v0, 0xffff8000, v0
	s_addc_u32 s1, s25, s1
	v_lshl_add_u32 v0, v18, 11, v0
	v_and_b32_e32 v1, 1, v17
	s_add_u32 s36, s6, 0x4080000
	v_lshl_or_b32 v0, v1, 6, v0
	s_addc_u32 s37, s1, 0
	v_lshl_add_u32 v140, v19, 1, v0
	v_lshlrev_b32_e32 v0, 14, v20
	s_cmpk_lt_u32 s0, 0x100
	v_and_b32_e32 v0, 0xffff8000, v0
	s_cselect_b64 s[38:39], -1, 0
	s_lshl_b32 s0, s16, 8
	v_lshl_add_u32 v0, v21, 11, v0
	v_and_b32_e32 v1, 1, v20
	s_add_i32 s84, s0, 0
	v_lshl_or_b32 v0, v1, 6, v0
	s_add_i32 s83, s84, 0x22400
	s_add_i32 s84, s84, 0x22600
	v_mov_b32_e32 v141, v201
	v_lshl_add_u32 v142, v22, 1, v0
	v_mov_b32_e32 v143, v201
	s_mov_b32 s85, 0
	v_add_u32_e32 v157, 0, v2
	s_branch .LBB0_1024

; __device__ __forceinline__ unsigned xb_ld(unsigned* p)              { return __hip_atomic_load(p, __ATOMIC_RELAXED, __HIP_MEMORY_SCOPE_AGENT); }
; __device__ __forceinline__ unsigned xb_add(unsigned* p, unsigned v) { return __hip_atomic_fetch_add(p, v, __ATOMIC_RELAXED, __HIP_MEMORY_SCOPE_AGENT); }
; #define XB_SPIN(cond, bar) do { unsigned _sp = 0; while (cond) { __builtin_amdgcn_s_sleep(1); \
;     if ((++_sp & 255u) == 0u) { if (xb_ld(&(bar)[XB_TMO])) break; if (_sp > XB_SPIN_CAP) { atomicAdd(&(bar)[XB_TMO], 1u); break; } } } } while (0)
; __device__ __forceinline__ void xcd_barrier_local(const XcdBarrier& b) {
;     ...
;         if (old + 1u == target) (void)xb_add(&bar[XB_XGEN(b.x)], 1u);
;         else XB_SPIN(xb_ld(&bar[XB_XSUB(b.x)]) < target, bar);
;         __builtin_amdgcn_fence(__ATOMIC_ACQUIRE, "agent");
;         asm volatile("s_waitcnt vmcnt(0)" ::: "memory");
;     }
.LBB0_1310:
	s_or_b64 exec, exec, s[0:1]
.LBB0_1311:
	s_or_b64 exec, exec, s[4:5]

; __device__ __forceinline__ unsigned xb_ld(unsigned* p)              { return __hip_atomic_load(p, __ATOMIC_RELAXED, __HIP_MEMORY_SCOPE_AGENT); }
; __device__ __forceinline__ unsigned xb_add(unsigned* p, unsigned v) { return __hip_atomic_fetch_add(p, v, __ATOMIC_RELAXED, __HIP_MEMORY_SCOPE_AGENT); }
; #define XB_SPIN(cond, bar) do { unsigned _sp = 0; while (cond) { __builtin_amdgcn_s_sleep(1); \
;     if ((++_sp & 255u) == 0u) { if (xb_ld(&(bar)[XB_TMO])) break; if (_sp > XB_SPIN_CAP) { atomicAdd(&(bar)[XB_TMO], 1u); break; } } } } while (0)
; __device__ __forceinline__ void xcd_barrier_local(const XcdBarrier& b) {
;     ...
;         if (old + 1u == target) (void)xb_add(&bar[XB_XGEN(b.x)], 1u);
;         else XB_SPIN(xb_ld(&bar[XB_XSUB(b.x)]) < target, bar);
;         __builtin_amdgcn_fence(__ATOMIC_ACQUIRE, "agent");
;         asm volatile("s_waitcnt vmcnt(0)" ::: "memory");
;     }
.LBB0_1691:
	s_or_b64 exec, exec, s[0:1]
.LBB0_1692:
	s_or_b64 exec, exec, s[2:3]

; #define PG8_STAGE(bufoff, gbase, voff) do { _Pragma("unroll") for (int _i = 0; _i < 2; ++_i) \
;         __builtin_amdgcn_global_load_lds((const unsigned*)((const char*)(gbase) + (voff)[_i]), (PG8_LAS unsigned*)(lds + (bufoff) + ldsw + _i * 8192), 16, 0, 0); } while (0)
; #define PG8_WAIT_V(n) asm volatile("s_waitcnt vmcnt(" #n ")" ::: "memory")
; #define PG8_BAR __builtin_amdgcn_s_barrier()
; __device__ __forceinline__ void unpack8(u32x4 w, f32x4& a, f32x4& b) { a = (f32x4){bflo(w.x), bfhi(w.x), bflo(w.y), bfhi(w.y)}; b = (f32x4){bflo(w.z), bfhi(w.z), bflo(w.w), bfhi(w.w)}; }
; template <class Epi, class Sched, bool ALIGN_EPI = false, bool SP2 = false>
; __device__ __forceinline__ void gemm_phase(PG8_LAS unsigned char* lds, const Gemm g, const Sched& S, const Epi& E, const int wave_id) {
;     ...
;         PG8_STAGE(PG8_SB(0, 0), cB, voffB); PG8_STAGE(PG8_SB(0, 1), cB + hstep, voffB); PG8_STAGE(PG8_SA(0, 0), cA, voffA); PG8_STAGE(PG8_SA(0, 1), cA + hstep, voffA);
;         if (wr == 1) PG8_BAR;
;         PG8_WAIT_V(2); PG8_BAR;
;         PG8_STAGE(PG8_SB(1, 0), cB + kstep, voffB); PG8_STAGE(PG8_SA(1, 0), cA + kstep, voffA); PG8_STAGE(PG8_SB(1, 1), cB + hstep + kstep, voffB);
;         PG8_WAIT_V(6); PG8_BAR;
;     } else {
;         PG8_STAGE(PG8_SB(0, 0), cB, voffB); PG8_STAGE(PG8_SA(0, 0), cA, voffA); PG8_STAGE(PG8_SB(0, 1), cB + hstep, voffB); PG8_STAGE(PG8_SA(0, 1), cA + hstep, voffA);
;         if (wr == 1) PG8_BAR;
;         PG8_WAIT_V(4); PG8_BAR;
;         PG8_STAGE(PG8_SB(1, 0), cB + kstep, voffB); PG8_STAGE(PG8_SA(1, 0), cA + kstep, voffA); PG8_STAGE(PG8_SB(1, 1), cB + hstep + kstep, voffB);
;         PG8_WAIT_V(6); PG8_BAR;
;     }
;     if constexpr (Epi::INIT_ACC) E.init_finish(acc, acc0);
;     __device__ __forceinline__ void init_finish(f32x4 (&acc)[2][2][4][2], const u32x4 (&old)[2][4][2]) const {
; #pragma unroll
;         for (int ai = 0; ai < 2; ++ai)
; #pragma unroll
;             for (int m = 0; m < 4; ++m)
; #pragma unroll
;                 for (int bj = 0; bj < 2; ++bj) unpack8(old[ai][m][bj], acc[ai][bj][m][0], acc[ai][bj][m][1]);
;     }
.LBB0_1708:
	v_or_b32_e32 v72, s47, v139
	v_lshlrev_b32_e32 v73, 4, v138
	v_lshlrev_b32_e32 v74, 6, v72
	s_movk_i32 s19, 0x3c0
	v_lshlrev_b32_e32 v72, 2, v72
	v_and_or_b32 v74, v74, s19, v73
	s_lshl_b32 s5, s5, 13
	v_and_b32_e32 v72, 32, v72
	s_add_i32 m0, s49, 0x18000
	v_lshl_add_u64 v[70:71], v[70:71], 0, s[88:89]
	v_bitop3_b32 v143, v74, s5, v72 bitop3:0xde
	s_lshl_b32 s5, s4, 12
	s_waitcnt vmcnt(2)
	s_barrier
	global_load_lds_dwordx4 v[70:71], off
	v_lshl_add_u64 v[68:69], v[68:69], 0, s[88:89]
	s_add_i32 m0, s49, 0x1a000
	s_add_i32 s53, s49, 0x8000
	s_add_i32 s54, s49, 0xa000
	global_load_lds_dwordx4 v[68:69], off
	v_lshl_add_u64 v[64:65], v[64:65], 0, s[88:89]
	s_mov_b32 m0, s53
	s_add_u32 s20, s34, 0x80080
	global_load_lds_dwordx4 v[64:65], off
	v_lshl_add_u64 v[64:65], v[66:67], 0, s[88:89]
	s_mov_b32 m0, s54
	s_addc_u32 s21, s35, 0
	global_load_lds_dwordx4 v[64:65], off
	s_add_i32 m0, s49, 0x1c000
	v_lshl_add_u64 v[64:65], s[20:21], 0, v[200:201]
	global_load_lds_dwordx4 v[64:65], off
	v_lshl_add_u64 v[64:65], s[20:21], 0, v[132:133]
	s_add_i32 m0, s49, 0x1e000
	v_lshlrev_b32_e32 v144, 15, v134
	global_load_lds_dwordx4 v[64:65], off
	v_and_b32_e32 v144, 0xffff0000, v144
	v_lshl_add_u32 v135, v135, 12, v144
	v_and_b32_e32 v134, 1, v134
	s_cmpk_lt_u32 s18, 0x100
	v_lshl_or_b32 v134, v134, 6, v135
	v_lshl_or_b32 v72, v139, 6, v73
	v_lshlrev_b32_e32 v73, 2, v139
	s_cselect_b64 s[18:19], -1, 0
	s_lshl_b32 s4, s4, 2
	v_lshl_add_u32 v134, v136, 1, v134
	v_lshlrev_b32_e32 v136, 15, v137
	v_and_b32_e32 v73, 32, v73
	s_add_u32 s4, s2, s4
	v_and_b32_e32 v136, 0xffff0000, v136
	v_bitop3_b32 v140, v72, s5, v73 bitop3:0xde
	s_waitcnt vmcnt(6)
	s_addc_u32 s5, s3, 0
	v_lshl_add_u32 v136, v141, 12, v136
	v_and_b32_e32 v137, 1, v137
	s_add_u32 s55, s4, 0x8900000
	v_lshl_or_b32 v136, v137, 6, v136
	s_waitcnt vmcnt(6)
	v_lshlrev_b32_e32 v112, 16, v60
	v_and_b32_e32 v113, 0xffff0000, v60
	v_lshlrev_b32_e32 v114, 16, v61
	v_and_b32_e32 v115, 0xffff0000, v61
	v_lshlrev_b32_e32 v116, 16, v62
	v_and_b32_e32 v117, 0xffff0000, v62
	v_lshlrev_b32_e32 v118, 16, v63
	v_and_b32_e32 v119, 0xffff0000, v63
	v_lshlrev_b32_e32 v120, 16, v52
	v_and_b32_e32 v121, 0xffff0000, v52
	v_lshlrev_b32_e32 v122, 16, v53
	v_and_b32_e32 v123, 0xffff0000, v53
	v_lshlrev_b32_e32 v124, 16, v54
	v_and_b32_e32 v125, 0xffff0000, v54
	v_lshlrev_b32_e32 v126, 16, v55
	v_and_b32_e32 v127, 0xffff0000, v55
	v_lshlrev_b32_e32 v96, 16, v56
	v_and_b32_e32 v97, 0xffff0000, v56
	v_lshlrev_b32_e32 v98, 16, v57
	v_and_b32_e32 v99, 0xffff0000, v57
	v_lshlrev_b32_e32 v100, 16, v58
	v_and_b32_e32 v101, 0xffff0000, v58
	v_lshlrev_b32_e32 v102, 16, v59
	v_and_b32_e32 v103, 0xffff0000, v59
	v_lshlrev_b32_e32 v104, 16, v44
	v_and_b32_e32 v105, 0xffff0000, v44
	v_lshlrev_b32_e32 v106, 16, v45
	v_and_b32_e32 v107, 0xffff0000, v45
	v_lshlrev_b32_e32 v108, 16, v46
	v_and_b32_e32 v109, 0xffff0000, v46
	v_lshlrev_b32_e32 v110, 16, v47
	v_and_b32_e32 v111, 0xffff0000, v47
	v_lshlrev_b32_e32 v80, 16, v48
	v_and_b32_e32 v81, 0xffff0000, v48
	v_lshlrev_b32_e32 v82, 16, v49
	v_and_b32_e32 v83, 0xffff0000, v49
	v_lshlrev_b32_e32 v84, 16, v50
	v_and_b32_e32 v85, 0xffff0000, v50
	v_lshlrev_b32_e32 v86, 16, v51
	v_and_b32_e32 v87, 0xffff0000, v51
	v_lshlrev_b32_e32 v88, 16, v36
	v_and_b32_e32 v89, 0xffff0000, v36
	v_lshlrev_b32_e32 v90, 16, v37
	v_and_b32_e32 v91, 0xffff0000, v37
	v_lshlrev_b32_e32 v92, 16, v38
	v_and_b32_e32 v93, 0xffff0000, v38
	v_lshlrev_b32_e32 v94, 16, v39
	v_and_b32_e32 v95, 0xffff0000, v39
	v_lshlrev_b32_e32 v60, 16, v40
	v_and_b32_e32 v61, 0xffff0000, v40
	v_lshlrev_b32_e32 v62, 16, v41
	v_and_b32_e32 v63, 0xffff0000, v41
	v_lshlrev_b32_e32 v68, 16, v42
	v_and_b32_e32 v69, 0xffff0000, v42
	v_lshlrev_b32_e32 v70, 16, v43
	v_and_b32_e32 v71, 0xffff0000, v43
	v_lshlrev_b32_e32 v72, 16, v28
	v_and_b32_e32 v73, 0xffff0000, v28
	v_lshlrev_b32_e32 v74, 16, v29
	v_and_b32_e32 v75, 0xffff0000, v29
	v_lshlrev_b32_e32 v76, 16, v30
	v_and_b32_e32 v77, 0xffff0000, v30
	v_lshlrev_b32_e32 v78, 16, v31
	v_and_b32_e32 v79, 0xffff0000, v31
	v_lshlrev_b32_e32 v48, 16, v32
	v_and_b32_e32 v49, 0xffff0000, v32
	v_lshlrev_b32_e32 v50, 16, v33
	v_and_b32_e32 v51, 0xffff0000, v33
	v_lshlrev_b32_e32 v52, 16, v34
	v_and_b32_e32 v53, 0xffff0000, v34
	v_lshlrev_b32_e32 v54, 16, v35
	v_and_b32_e32 v55, 0xffff0000, v35
	v_lshlrev_b32_e32 v56, 16, v16
	v_and_b32_e32 v57, 0xffff0000, v16
	v_lshlrev_b32_e32 v58, 16, v17
	v_and_b32_e32 v59, 0xffff0000, v17
	v_lshlrev_b32_e32 v64, 16, v18
	v_and_b32_e32 v65, 0xffff0000, v18
	v_lshlrev_b32_e32 v66, 16, v19
	v_and_b32_e32 v67, 0xffff0000, v19
	v_lshlrev_b32_e32 v32, 16, v24
	v_and_b32_e32 v33, 0xffff0000, v24
	v_lshlrev_b32_e32 v34, 16, v25
	v_and_b32_e32 v35, 0xffff0000, v25
	v_lshlrev_b32_e32 v36, 16, v26
	v_and_b32_e32 v37, 0xffff0000, v26
	v_lshlrev_b32_e32 v38, 16, v27
	v_and_b32_e32 v39, 0xffff0000, v27
	v_lshlrev_b32_e32 v40, 16, v8
	v_and_b32_e32 v41, 0xffff0000, v8
	v_lshlrev_b32_e32 v42, 16, v9
	v_and_b32_e32 v43, 0xffff0000, v9
	v_lshlrev_b32_e32 v44, 16, v10
	v_and_b32_e32 v45, 0xffff0000, v10
	v_lshlrev_b32_e32 v46, 16, v11
	v_and_b32_e32 v47, 0xffff0000, v11
	v_lshlrev_b32_e32 v16, 16, v20
	v_and_b32_e32 v17, 0xffff0000, v20
	v_lshlrev_b32_e32 v18, 16, v21
	v_and_b32_e32 v19, 0xffff0000, v21
	v_lshlrev_b32_e32 v20, 16, v22
	v_and_b32_e32 v21, 0xffff0000, v22
	v_lshlrev_b32_e32 v22, 16, v23
	v_and_b32_e32 v23, 0xffff0000, v23
	v_lshlrev_b32_e32 v24, 16, v0
	v_and_b32_e32 v25, 0xffff0000, v0
	v_lshlrev_b32_e32 v26, 16, v1
	v_and_b32_e32 v27, 0xffff0000, v1
	v_lshlrev_b32_e32 v28, 16, v2
	v_and_b32_e32 v29, 0xffff0000, v2
	v_lshlrev_b32_e32 v30, 16, v3
	v_and_b32_e32 v31, 0xffff0000, v3
	v_lshlrev_b32_e32 v0, 16, v4
	v_and_b32_e32 v1, 0xffff0000, v4
	v_lshlrev_b32_e32 v2, 16, v5
	v_and_b32_e32 v3, 0xffff0000, v5
	v_lshlrev_b32_e32 v4, 16, v6
	v_and_b32_e32 v5, 0xffff0000, v6
	v_lshlrev_b32_e32 v6, 16, v7
	v_and_b32_e32 v7, 0xffff0000, v7
	v_lshlrev_b32_e32 v8, 16, v12
	v_and_b32_e32 v9, 0xffff0000, v12
	v_lshlrev_b32_e32 v10, 16, v13
	v_and_b32_e32 v11, 0xffff0000, v13
	v_lshlrev_b32_e32 v12, 16, v14
	v_and_b32_e32 v13, 0xffff0000, v14
	v_lshlrev_b32_e32 v14, 16, v15
	v_and_b32_e32 v15, 0xffff0000, v15
	s_addc_u32 s56, s5, 0
	s_ashr_i32 s57, s42, 31
	s_ashr_i32 s58, s43, 31
	v_mov_b32_e32 v135, v201
	v_lshl_add_u32 v136, v142, 1, v136
	v_mov_b32_e32 v137, v201
	s_mov_b32 s59, 0
	v_add_u32_e32 v141, 0, v143
	s_barrier
	s_branch .LBB0_1711

; __device__ __forceinline__ unsigned xb_ld(unsigned* p)              { return __hip_atomic_load(p, __ATOMIC_RELAXED, __HIP_MEMORY_SCOPE_AGENT); }
; __device__ __forceinline__ unsigned xb_add(unsigned* p, unsigned v) { return __hip_atomic_fetch_add(p, v, __ATOMIC_RELAXED, __HIP_MEMORY_SCOPE_AGENT); }
; #define XB_SPIN(cond, bar) do { unsigned _sp = 0; while (cond) { __builtin_amdgcn_s_sleep(1); \
;     if ((++_sp & 255u) == 0u) { if (xb_ld(&(bar)[XB_TMO])) break; if (_sp > XB_SPIN_CAP) { atomicAdd(&(bar)[XB_TMO], 1u); break; } } } } while (0)
; __device__ __forceinline__ void xcd_barrier_local(const XcdBarrier& b) {
;     ...
;         if (old + 1u == target) (void)xb_add(&bar[XB_XGEN(b.x)], 1u);
;         else XB_SPIN(xb_ld(&bar[XB_XSUB(b.x)]) < target, bar);
;         __builtin_amdgcn_fence(__ATOMIC_ACQUIRE, "agent");
;         asm volatile("s_waitcnt vmcnt(0)" ::: "memory");
;     }
.LBB0_1831:
	s_or_b64 exec, exec, s[0:1]
.LBB0_1832:
	s_or_b64 exec, exec, s[4:5]

; #define PG8_STAGE(bufoff, gbase, voff) do { _Pragma("unroll") for (int _i = 0; _i < 2; ++_i) \
;         __builtin_amdgcn_global_load_lds((const unsigned*)((const char*)(gbase) + (voff)[_i]), (PG8_LAS unsigned*)(lds + (bufoff) + ldsw + _i * 8192), 16, 0, 0); } while (0)
; #define PG8_WAIT_V(n) asm volatile("s_waitcnt vmcnt(" #n ")" ::: "memory")
; #define PG8_BAR __builtin_amdgcn_s_barrier()
; #define LAS __attribute__((address_space(3)))
; template <class Epi, class Sched, bool ALIGN_EPI = false, bool SP2 = false>
; __device__ __forceinline__ void gemm_phase(PG8_LAS unsigned char* lds, const Gemm g, const Sched& S, const Epi& E, const int wave_id) {
;     ...
;         PG8_STAGE(PG8_SB(0, 0), cB, voffB); PG8_STAGE(PG8_SB(0, 1), cB + hstep, voffB); PG8_STAGE(PG8_SA(0, 0), cA, voffA); PG8_STAGE(PG8_SA(0, 1), cA + hstep, voffA);
;         if (wr == 1) PG8_BAR;
;         PG8_WAIT_V(2); PG8_BAR;
;         PG8_STAGE(PG8_SB(1, 0), cB + kstep, voffB); PG8_STAGE(PG8_SA(1, 0), cA + kstep, voffA); PG8_STAGE(PG8_SB(1, 1), cB + hstep + kstep, voffB);
;         PG8_WAIT_V(6); PG8_BAR;
;     } else {
;         PG8_STAGE(PG8_SB(0, 0), cB, voffB); PG8_STAGE(PG8_SA(0, 0), cA, voffA); PG8_STAGE(PG8_SB(0, 1), cB + hstep, voffB); PG8_STAGE(PG8_SA(0, 1), cA + hstep, voffA);
;         if (wr == 1) PG8_BAR;
;         PG8_WAIT_V(4); PG8_BAR;
;         PG8_STAGE(PG8_SB(1, 0), cB + kstep, voffB); PG8_STAGE(PG8_SA(1, 0), cA + kstep, voffA); PG8_STAGE(PG8_SB(1, 1), cB + hstep + kstep, voffB);
;         PG8_WAIT_V(6); PG8_BAR;
;     }
;     if constexpr (Epi::INIT_ACC) E.init_finish(acc, acc0);
;     if constexpr (Epi::PRE_TAB) E.pre_finish(pre4, prec, tid);
;     __device__ __forceinline__ void pre_finish(const f32x4 (&p)[4], const float (&c)[3], int tid) const {
;         if (tid < 256) { const f32x4 s4 = (p[0] + p[1]) + (p[2] + p[3]); ((LAS float*)rtab)[tid] = rsqrtf(((s4[0] + s4[1]) + (s4[2] + s4[3])) * (1.0f / D) + EPS); }
;     }
.LBB0_1851:
	v_lshl_add_u64 v[24:25], s[40:41], 0, v[200:201]
	v_mov_b32_e32 v133, v201
	v_lshl_add_u64 v[26:27], s[40:41], 0, v[132:133]
	v_mov_b32_e32 v129, v201
	s_add_i32 m0, s51, 0x18000
	v_lshl_add_u64 v[24:25], v[24:25], 0, s[88:89]
	v_lshl_add_u64 v[28:29], s[38:39], 0, v[128:129]
	v_mov_b32_e32 v131, v201
	s_waitcnt vmcnt(2)
	s_barrier
	global_load_lds_dwordx4 v[24:25], off
	v_lshl_add_u64 v[24:25], v[26:27], 0, s[88:89]
	s_add_i32 m0, s51, 0x1a000
	s_add_i32 s55, s51, 0x8000
	s_add_i32 s56, s51, 0xa000
	v_lshl_add_u64 v[30:31], s[38:39], 0, v[130:131]
	global_load_lds_dwordx4 v[24:25], off
	v_lshl_add_u64 v[24:25], v[28:29], 0, s[88:89]
	s_mov_b32 m0, s55
	s_add_u32 s4, s40, 0x40080
	global_load_lds_dwordx4 v[24:25], off
	v_lshl_add_u64 v[24:25], v[30:31], 0, s[88:89]
	s_mov_b32 m0, s56
	s_addc_u32 s5, s41, 0
	global_load_lds_dwordx4 v[24:25], off
	s_add_i32 m0, s51, 0x1c000
	v_lshl_add_u64 v[24:25], s[4:5], 0, v[200:201]
	global_load_lds_dwordx4 v[24:25], off
	v_lshl_add_u64 v[24:25], s[4:5], 0, v[132:133]
	s_add_i32 m0, s51, 0x1e000
	s_nop 0
	global_load_lds_dwordx4 v[24:25], off
	s_waitcnt vmcnt(6)
	s_barrier
	s_and_saveexec_b64 s[4:5], vcc
	s_cbranch_execz .LBB0_1853
	s_waitcnt vmcnt(6)
	v_pk_add_f32 v[8:9], v[8:9], v[12:13]
	v_pk_add_f32 v[10:11], v[10:11], v[14:15]
	v_pk_add_f32 v[0:1], v[0:1], v[4:5]
	v_pk_add_f32 v[2:3], v[2:3], v[6:7]
	v_pk_add_f32 v[0:1], v[0:1], v[8:9]
	v_pk_add_f32 v[2:3], v[2:3], v[10:11]
	s_mov_b32 s7, 0x800000
	v_pk_mov_b32 v[4:5], v[0:1], v[2:3] op_sel:[1,0]
	v_mov_b32_e32 v1, v3
	v_pk_add_f32 v[0:1], v[4:5], v[0:1]
	s_nop 0
	v_add_f32_e32 v0, v0, v1
	v_mov_b32_e32 v1, 0x358637bd
	v_fmamk_f32 v0, v0, 0x3a800000, v1
	v_mul_f32_e32 v1, 0x4b800000, v0
	v_cmp_gt_f32_e32 vcc, s7, v0
	s_nop 1
	v_cndmask_b32_e32 v0, v0, v1, vcc
	v_rsq_f32_e32 v0, v0
	s_nop 0
	v_mul_f32_e32 v1, 0x45800000, v0
	v_cndmask_b32_e32 v0, v0, v1, vcc
	v_lshl_add_u32 v1, v16, 2, 0
	v_add_u32_e32 v1, 0x22400, v1
	ds_write_b32 v1, v0
.LBB0_1853:
	s_or_b64 exec, exec, s[4:5]
	v_bfe_u32 v144, v16, 4, 2
	s_add_u32 s22, s2, 0x14c00000
	v_and_b32_e32 v143, 15, v16
	s_waitcnt vmcnt(6)
	v_lshlrev_b32_e32 v0, 4, v144
	v_lshlrev_b32_e32 v1, 2, v16
	s_addc_u32 s23, s3, 0
	v_lshl_or_b32 v0, v143, 6, v0
	s_lshl_b32 s4, s26, 13
	v_and_b32_e32 v1, 32, v1
	v_bitop3_b32 v2, v0, s4, v1 bitop3:0xde
	s_lshl_b32 s4, s25, 5
	s_and_b32 s59, s4, 0x60
	s_lshl_b32 s4, s59, 7
	v_bitop3_b32 v145, v0, s4, v1 bitop3:0xde
	v_lshlrev_b32_e32 v0, 14, v17
	v_and_b32_e32 v0, 0xffff8000, v0
	v_lshl_add_u32 v0, v18, 11, v0
	v_and_b32_e32 v1, 1, v17
	v_lshl_or_b32 v0, v1, 6, v0
	s_ashr_i32 s57, s46, 31
	s_lshl_b32 s58, s26, 6
	v_lshl_add_u32 v134, v19, 1, v0
	v_lshlrev_b32_e32 v0, 14, v20
	s_cmpk_lt_u32 s24, 0x100
	v_and_b32_e32 v0, 0xffff8000, v0
	s_cselect_b64 s[24:25], -1, 0
	s_lshl_b32 s4, s26, 8
	v_lshl_add_u32 v0, v21, 11, v0
	v_and_b32_e32 v1, 1, v20
	s_add_i32 s61, s4, 0
	v_lshl_or_b32 v0, v1, 6, v0
	s_add_i32 s60, s61, 0x22400
	s_add_i32 s61, s61, 0x22600
	v_mov_b32_e32 v135, v201
	v_lshl_add_u32 v136, v22, 1, v0
	v_mov_b32_e32 v137, v201
	s_mov_b32 s62, 0
	v_add_u32_e32 v146, 0, v2
	s_branch .LBB0_1856

; __device__ __forceinline__ unsigned xb_ld(unsigned* p)              { return __hip_atomic_load(p, __ATOMIC_RELAXED, __HIP_MEMORY_SCOPE_AGENT); }
; __device__ __forceinline__ unsigned xb_add(unsigned* p, unsigned v) { return __hip_atomic_fetch_add(p, v, __ATOMIC_RELAXED, __HIP_MEMORY_SCOPE_AGENT); }
; #define XB_SPIN(cond, bar) do { unsigned _sp = 0; while (cond) { __builtin_amdgcn_s_sleep(1); \
;     if ((++_sp & 255u) == 0u) { if (xb_ld(&(bar)[XB_TMO])) break; if (_sp > XB_SPIN_CAP) { atomicAdd(&(bar)[XB_TMO], 1u); break; } } } } while (0)
; __device__ __forceinline__ void xcd_barrier_local(const XcdBarrier& b) {
;     ...
;         if (old + 1u == target) (void)xb_add(&bar[XB_XGEN(b.x)], 1u);
;         else XB_SPIN(xb_ld(&bar[XB_XSUB(b.x)]) < target, bar);
;         __builtin_amdgcn_fence(__ATOMIC_ACQUIRE, "agent");
;         asm volatile("s_waitcnt vmcnt(0)" ::: "memory");
;     }
.LBB0_1991:
	s_or_b64 exec, exec, s[0:1]
.LBB0_1992:
	s_or_b64 exec, exec, s[4:5]

; __device__ __forceinline__ unsigned xb_ld(unsigned* p)              { return __hip_atomic_load(p, __ATOMIC_RELAXED, __HIP_MEMORY_SCOPE_AGENT); }
; __device__ __forceinline__ unsigned xb_add(unsigned* p, unsigned v) { return __hip_atomic_fetch_add(p, v, __ATOMIC_RELAXED, __HIP_MEMORY_SCOPE_AGENT); }
; #define XB_SPIN(cond, bar) do { unsigned _sp = 0; while (cond) { __builtin_amdgcn_s_sleep(1); \
;     if ((++_sp & 255u) == 0u) { if (xb_ld(&(bar)[XB_TMO])) break; if (_sp > XB_SPIN_CAP) { atomicAdd(&(bar)[XB_TMO], 1u); break; } } } } while (0)
; __device__ __forceinline__ void xcd_barrier_local(const XcdBarrier& b) {
;     ...
;         if (old + 1u == target) (void)xb_add(&bar[XB_XGEN(b.x)], 1u);
;         else XB_SPIN(xb_ld(&bar[XB_XSUB(b.x)]) < target, bar);
;         __builtin_amdgcn_fence(__ATOMIC_ACQUIRE, "agent");
;         asm volatile("s_waitcnt vmcnt(0)" ::: "memory");
;     }
.LBB0_2211:
	s_or_b64 exec, exec, s[0:1]
.LBB0_2212:
	s_or_b64 exec, exec, s[4:5]

; #define PG8_STAGE(bufoff, gbase, voff) do { _Pragma("unroll") for (int _i = 0; _i < 2; ++_i) \
;         __builtin_amdgcn_global_load_lds((const unsigned*)((const char*)(gbase) + (voff)[_i]), (PG8_LAS unsigned*)(lds + (bufoff) + ldsw + _i * 8192), 16, 0, 0); } while (0)
; #define PG8_WAIT_V(n) asm volatile("s_waitcnt vmcnt(" #n ")" ::: "memory")
; #define PG8_BAR __builtin_amdgcn_s_barrier()
; __device__ __forceinline__ void unpack8(u32x4 w, f32x4& a, f32x4& b) { a = (f32x4){bflo(w.x), bfhi(w.x), bflo(w.y), bfhi(w.y)}; b = (f32x4){bflo(w.z), bfhi(w.z), bflo(w.w), bfhi(w.w)}; }
; template <class Epi, class Sched, bool ALIGN_EPI = false, bool SP2 = false>
; __device__ __forceinline__ void gemm_phase(PG8_LAS unsigned char* lds, const Gemm g, const Sched& S, const Epi& E, const int wave_id) {
;     ...
;         PG8_STAGE(PG8_SB(0, 0), cB, voffB); PG8_STAGE(PG8_SB(0, 1), cB + hstep, voffB); PG8_STAGE(PG8_SA(0, 0), cA, voffA); PG8_STAGE(PG8_SA(0, 1), cA + hstep, voffA);
;         if (wr == 1) PG8_BAR;
;         PG8_WAIT_V(2); PG8_BAR;
;         PG8_STAGE(PG8_SB(1, 0), cB + kstep, voffB); PG8_STAGE(PG8_SA(1, 0), cA + kstep, voffA); PG8_STAGE(PG8_SB(1, 1), cB + hstep + kstep, voffB);
;         PG8_WAIT_V(6); PG8_BAR;
;     } else {
;         PG8_STAGE(PG8_SB(0, 0), cB, voffB); PG8_STAGE(PG8_SA(0, 0), cA, voffA); PG8_STAGE(PG8_SB(0, 1), cB + hstep, voffB); PG8_STAGE(PG8_SA(0, 1), cA + hstep, voffA);
;         if (wr == 1) PG8_BAR;
;         PG8_WAIT_V(4); PG8_BAR;
;         PG8_STAGE(PG8_SB(1, 0), cB + kstep, voffB); PG8_STAGE(PG8_SA(1, 0), cA + kstep, voffA); PG8_STAGE(PG8_SB(1, 1), cB + hstep + kstep, voffB);
;         PG8_WAIT_V(6); PG8_BAR;
;     }
;     if constexpr (Epi::INIT_ACC) E.init_finish(acc, acc0);
;     __device__ __forceinline__ void init_finish(f32x4 (&acc)[2][2][4][2], const u32x4 (&old)[2][4][2]) const {
; #pragma unroll
;         for (int ai = 0; ai < 2; ++ai)
; #pragma unroll
;             for (int m = 0; m < 4; ++m)
; #pragma unroll
;                 for (int bj = 0; bj < 2; ++bj) unpack8(old[ai][m][bj], acc[ai][bj][m][0], acc[ai][bj][m][1]);
;     }
.LBB0_2227:
	v_or_b32_e32 v72, s47, v139
	v_lshlrev_b32_e32 v73, 4, v138
	v_lshlrev_b32_e32 v74, 6, v72
	s_movk_i32 s19, 0x3c0
	v_lshlrev_b32_e32 v72, 2, v72
	v_and_or_b32 v74, v74, s19, v73
	s_lshl_b32 s5, s5, 13
	v_and_b32_e32 v72, 32, v72
	s_add_i32 m0, s49, 0x18000
	v_lshl_add_u64 v[70:71], v[70:71], 0, s[88:89]
	v_bitop3_b32 v143, v74, s5, v72 bitop3:0xde
	s_lshl_b32 s5, s4, 12
	s_waitcnt vmcnt(2)
	s_barrier
	global_load_lds_dwordx4 v[70:71], off
	v_lshl_add_u64 v[68:69], v[68:69], 0, s[88:89]
	s_add_i32 m0, s49, 0x1a000
	s_add_i32 s53, s49, 0x8000
	s_add_i32 s54, s49, 0xa000
	global_load_lds_dwordx4 v[68:69], off
	v_lshl_add_u64 v[64:65], v[64:65], 0, s[88:89]
	s_mov_b32 m0, s53
	s_add_u32 s20, s34, 0x40080
	global_load_lds_dwordx4 v[64:65], off
	v_lshl_add_u64 v[64:65], v[66:67], 0, s[88:89]
	s_mov_b32 m0, s54
	s_addc_u32 s21, s35, 0
	global_load_lds_dwordx4 v[64:65], off
	s_add_i32 m0, s49, 0x1c000
	v_lshl_add_u64 v[64:65], s[20:21], 0, v[200:201]
	global_load_lds_dwordx4 v[64:65], off
	v_lshl_add_u64 v[64:65], s[20:21], 0, v[132:133]
	s_add_i32 m0, s49, 0x1e000
	v_lshlrev_b32_e32 v144, 14, v134
	global_load_lds_dwordx4 v[64:65], off
	v_and_b32_e32 v144, 0xffff8000, v144
	v_lshl_add_u32 v135, v135, 11, v144
	v_and_b32_e32 v134, 1, v134
	s_cmpk_lt_u32 s18, 0x100
	v_lshl_or_b32 v134, v134, 6, v135
	v_lshl_or_b32 v72, v139, 6, v73
	v_lshlrev_b32_e32 v73, 2, v139
	s_cselect_b64 s[18:19], -1, 0
	s_lshl_b32 s4, s4, 2
	v_lshl_add_u32 v134, v136, 1, v134
	v_lshlrev_b32_e32 v136, 14, v137
	v_and_b32_e32 v73, 32, v73
	s_add_u32 s4, s2, s4
	v_and_b32_e32 v136, 0xffff8000, v136
	v_bitop3_b32 v140, v72, s5, v73 bitop3:0xde
	s_waitcnt vmcnt(6)
	s_addc_u32 s5, s3, 0
	v_lshl_add_u32 v136, v141, 11, v136
	v_and_b32_e32 v137, 1, v137
	s_add_u32 s55, s4, 0x8900000
	v_lshl_or_b32 v136, v137, 6, v136
	s_waitcnt vmcnt(6)
	v_lshlrev_b32_e32 v112, 16, v60
	v_and_b32_e32 v113, 0xffff0000, v60
	v_lshlrev_b32_e32 v114, 16, v61
	v_and_b32_e32 v115, 0xffff0000, v61
	v_lshlrev_b32_e32 v116, 16, v62
	v_and_b32_e32 v117, 0xffff0000, v62
	v_lshlrev_b32_e32 v118, 16, v63
	v_and_b32_e32 v119, 0xffff0000, v63
	v_lshlrev_b32_e32 v120, 16, v52
	v_and_b32_e32 v121, 0xffff0000, v52
	v_lshlrev_b32_e32 v122, 16, v53
	v_and_b32_e32 v123, 0xffff0000, v53
	v_lshlrev_b32_e32 v124, 16, v54
	v_and_b32_e32 v125, 0xffff0000, v54
	v_lshlrev_b32_e32 v126, 16, v55
	v_and_b32_e32 v127, 0xffff0000, v55
	v_lshlrev_b32_e32 v96, 16, v56
	v_and_b32_e32 v97, 0xffff0000, v56
	v_lshlrev_b32_e32 v98, 16, v57
	v_and_b32_e32 v99, 0xffff0000, v57
	v_lshlrev_b32_e32 v100, 16, v58
	v_and_b32_e32 v101, 0xffff0000, v58
	v_lshlrev_b32_e32 v102, 16, v59
	v_and_b32_e32 v103, 0xffff0000, v59
	v_lshlrev_b32_e32 v104, 16, v44
	v_and_b32_e32 v105, 0xffff0000, v44
	v_lshlrev_b32_e32 v106, 16, v45
	v_and_b32_e32 v107, 0xffff0000, v45
	v_lshlrev_b32_e32 v108, 16, v46
	v_and_b32_e32 v109, 0xffff0000, v46
	v_lshlrev_b32_e32 v110, 16, v47
	v_and_b32_e32 v111, 0xffff0000, v47
	v_lshlrev_b32_e32 v80, 16, v48
	v_and_b32_e32 v81, 0xffff0000, v48
	v_lshlrev_b32_e32 v82, 16, v49
	v_and_b32_e32 v83, 0xffff0000, v49
	v_lshlrev_b32_e32 v84, 16, v50
	v_and_b32_e32 v85, 0xffff0000, v50
	v_lshlrev_b32_e32 v86, 16, v51
	v_and_b32_e32 v87, 0xffff0000, v51
	v_lshlrev_b32_e32 v88, 16, v36
	v_and_b32_e32 v89, 0xffff0000, v36
	v_lshlrev_b32_e32 v90, 16, v37
	v_and_b32_e32 v91, 0xffff0000, v37
	v_lshlrev_b32_e32 v92, 16, v38
	v_and_b32_e32 v93, 0xffff0000, v38
	v_lshlrev_b32_e32 v94, 16, v39
	v_and_b32_e32 v95, 0xffff0000, v39
	v_lshlrev_b32_e32 v60, 16, v40
	v_and_b32_e32 v61, 0xffff0000, v40
	v_lshlrev_b32_e32 v62, 16, v41
	v_and_b32_e32 v63, 0xffff0000, v41
	v_lshlrev_b32_e32 v68, 16, v42
	v_and_b32_e32 v69, 0xffff0000, v42
	v_lshlrev_b32_e32 v70, 16, v43
	v_and_b32_e32 v71, 0xffff0000, v43
	v_lshlrev_b32_e32 v72, 16, v28
	v_and_b32_e32 v73, 0xffff0000, v28
	v_lshlrev_b32_e32 v74, 16, v29
	v_and_b32_e32 v75, 0xffff0000, v29
	v_lshlrev_b32_e32 v76, 16, v30
	v_and_b32_e32 v77, 0xffff0000, v30
	v_lshlrev_b32_e32 v78, 16, v31
	v_and_b32_e32 v79, 0xffff0000, v31
	v_lshlrev_b32_e32 v48, 16, v32
	v_and_b32_e32 v49, 0xffff0000, v32
	v_lshlrev_b32_e32 v50, 16, v33
	v_and_b32_e32 v51, 0xffff0000, v33
	v_lshlrev_b32_e32 v52, 16, v34
	v_and_b32_e32 v53, 0xffff0000, v34
	v_lshlrev_b32_e32 v54, 16, v35
	v_and_b32_e32 v55, 0xffff0000, v35
	v_lshlrev_b32_e32 v56, 16, v16
	v_and_b32_e32 v57, 0xffff0000, v16
	v_lshlrev_b32_e32 v58, 16, v17
	v_and_b32_e32 v59, 0xffff0000, v17
	v_lshlrev_b32_e32 v64, 16, v18
	v_and_b32_e32 v65, 0xffff0000, v18
	v_lshlrev_b32_e32 v66, 16, v19
	v_and_b32_e32 v67, 0xffff0000, v19
	v_lshlrev_b32_e32 v32, 16, v24
	v_and_b32_e32 v33, 0xffff0000, v24
	v_lshlrev_b32_e32 v34, 16, v25
	v_and_b32_e32 v35, 0xffff0000, v25
	v_lshlrev_b32_e32 v36, 16, v26
	v_and_b32_e32 v37, 0xffff0000, v26
	v_lshlrev_b32_e32 v38, 16, v27
	v_and_b32_e32 v39, 0xffff0000, v27
	v_lshlrev_b32_e32 v40, 16, v8
	v_and_b32_e32 v41, 0xffff0000, v8
	v_lshlrev_b32_e32 v42, 16, v9
	v_and_b32_e32 v43, 0xffff0000, v9
	v_lshlrev_b32_e32 v44, 16, v10
	v_and_b32_e32 v45, 0xffff0000, v10
	v_lshlrev_b32_e32 v46, 16, v11
	v_and_b32_e32 v47, 0xffff0000, v11
	v_lshlrev_b32_e32 v16, 16, v20
	v_and_b32_e32 v17, 0xffff0000, v20
	v_lshlrev_b32_e32 v18, 16, v21
	v_and_b32_e32 v19, 0xffff0000, v21
	v_lshlrev_b32_e32 v20, 16, v22
	v_and_b32_e32 v21, 0xffff0000, v22
	v_lshlrev_b32_e32 v22, 16, v23
	v_and_b32_e32 v23, 0xffff0000, v23
	v_lshlrev_b32_e32 v24, 16, v0
	v_and_b32_e32 v25, 0xffff0000, v0
	v_lshlrev_b32_e32 v26, 16, v1
	v_and_b32_e32 v27, 0xffff0000, v1
	v_lshlrev_b32_e32 v28, 16, v2
	v_and_b32_e32 v29, 0xffff0000, v2
	v_lshlrev_b32_e32 v30, 16, v3
	v_and_b32_e32 v31, 0xffff0000, v3
	v_lshlrev_b32_e32 v0, 16, v4
	v_and_b32_e32 v1, 0xffff0000, v4
	v_lshlrev_b32_e32 v2, 16, v5
	v_and_b32_e32 v3, 0xffff0000, v5
	v_lshlrev_b32_e32 v4, 16, v6
	v_and_b32_e32 v5, 0xffff0000, v6
	v_lshlrev_b32_e32 v6, 16, v7
	v_and_b32_e32 v7, 0xffff0000, v7
	v_lshlrev_b32_e32 v8, 16, v12
	v_and_b32_e32 v9, 0xffff0000, v12
	v_lshlrev_b32_e32 v10, 16, v13
	v_and_b32_e32 v11, 0xffff0000, v13
	v_lshlrev_b32_e32 v12, 16, v14
	v_and_b32_e32 v13, 0xffff0000, v14
	v_lshlrev_b32_e32 v14, 16, v15
	v_and_b32_e32 v15, 0xffff0000, v15
	s_addc_u32 s56, s5, 0
	s_ashr_i32 s57, s42, 31
	s_ashr_i32 s58, s43, 31
	v_mov_b32_e32 v135, v201
	v_lshl_add_u32 v136, v142, 1, v136
	v_mov_b32_e32 v137, v201
	s_mov_b32 s59, 0
	v_add_u32_e32 v141, 0, v143
	s_barrier
	s_branch .LBB0_2230

; __device__ __forceinline__ unsigned xb_ld(unsigned* p)              { return __hip_atomic_load(p, __ATOMIC_RELAXED, __HIP_MEMORY_SCOPE_AGENT); }
; __device__ __forceinline__ unsigned xb_add(unsigned* p, unsigned v) { return __hip_atomic_fetch_add(p, v, __ATOMIC_RELAXED, __HIP_MEMORY_SCOPE_AGENT); }
; #define XB_SPIN(cond, bar) do { unsigned _sp = 0; while (cond) { __builtin_amdgcn_s_sleep(1); \
;     if ((++_sp & 255u) == 0u) { if (xb_ld(&(bar)[XB_TMO])) break; if (_sp > XB_SPIN_CAP) { atomicAdd(&(bar)[XB_TMO], 1u); break; } } } } while (0)
; __device__ __forceinline__ void xcd_barrier_local(const XcdBarrier& b) {
;     ...
;         if (old + 1u == target) (void)xb_add(&bar[XB_XGEN(b.x)], 1u);
;         else XB_SPIN(xb_ld(&bar[XB_XSUB(b.x)]) < target, bar);
;         __builtin_amdgcn_fence(__ATOMIC_ACQUIRE, "agent");
;         asm volatile("s_waitcnt vmcnt(0)" ::: "memory");
;     }
.LBB0_2351:
	s_or_b64 exec, exec, s[0:1]
.LBB0_2352:
	s_or_b64 exec, exec, s[2:3]
